# SO1+cvtpk + attention tile loop hand-rewritten: software-pipelined (QK of tile t+1 with PV of tile t, loads 2 tiles ahead), fewer waits/SALU per tile
# speedup vs baseline: 1.0082x; 1.0082x over previous
.LBB0_987:
	s_waitcnt lgkmcnt(0)
	v_add_f32_e32 v2, v2, v3
	v_mul_f32_e32 v3, 0x4f800000, v2
	v_cmp_gt_f32_e32 vcc, s36, v2
	s_lshl_b32 s26, s42, 7
	s_add_i32 s42, s29, 0x2000
	v_cndmask_b32_e32 v2, v2, v3, vcc
	v_sqrt_f32_e32 v3, v2
	v_mov_b32_e32 v139, 0
	v_lshl_add_u32 v141, s41, 13, v154
	v_mov_b32_e32 v7, v139
	v_add_u32_e32 v5, -1, v3
	v_fma_f32 v6, -v5, v3, v2
	v_cmp_ge_f32_e64 s[4:5], 0, v6
	v_add_u32_e32 v6, 1, v3
	v_mov_b32_e32 v8, v139
	v_cndmask_b32_e64 v5, v3, v5, s[4:5]
	v_fma_f32 v3, -v6, v3, v2
	v_cmp_lt_f32_e64 s[4:5], 0, v3
	v_mov_b32_e32 v9, v139
	v_mov_b32_e32 v10, v139
	v_cndmask_b32_e64 v3, v5, v6, s[4:5]
	v_mul_f32_e32 v5, 0x37800000, v3
	v_cndmask_b32_e32 v3, v3, v5, vcc
	v_cmp_class_f32_e32 vcc, v2, v156
	s_add_i32 s4, s44, 1
	s_and_b32 s5, s45, 0x3ffffff0
	v_cndmask_b32_e32 v2, v3, v2, vcc
	v_mul_f32_e64 v66, v2, -v4
	v_lshl_add_u64 v[2:3], s[22:23], 0, v[134:135]
	s_add_u32 s22, s6, s5
	s_addc_u32 s23, 0, 0
	v_lshl_add_u64 v[144:145], v[2:3], 0, s[22:23]
	s_add_u32 s22, s6, s28
	s_addc_u32 s23, 0, 0
	s_lshl_b32 s5, s43, 9
	s_and_b32 s5, s5, 0x18000
	v_lshl_or_b32 v4, v155, 1, s5
	v_mov_b32_e32 v5, v131
	v_lshl_add_u64 v[2:3], s[24:25], 0, v[136:137]
	v_lshl_add_u64 v[4:5], s[22:23], 0, v[4:5]
	v_mov_b32_e32 v67, v66
	v_mov_b32_e32 v68, v66
	v_mov_b32_e32 v69, v66
	v_mov_b32_e32 v70, v66
	v_mov_b32_e32 v71, v66
	v_mov_b32_e32 v72, v66
	v_mov_b32_e32 v73, v66
	v_mov_b32_e32 v74, v66
	v_mov_b32_e32 v75, v66
	v_mov_b32_e32 v76, v66
	v_mov_b32_e32 v77, v66
	v_mov_b32_e32 v78, v66
	v_mov_b32_e32 v79, v66
	v_mov_b32_e32 v80, v66
	v_mov_b32_e32 v81, v66
	v_lshl_add_u64 v[146:147], v[2:3], 0, v[4:5]
	s_mov_b32 s6, 0
	v_mov_b32_e32 v2, 0
	v_mov_b32_e32 v3, v139
	v_mov_b32_e32 v4, v139
	v_mov_b32_e32 v5, v139
	v_mov_b32_e32 v6, v139
	v_mov_b32_e32 v11, v139
	v_mov_b32_e32 v12, v139
	v_mov_b32_e32 v13, v139
	v_mov_b32_e32 v14, v139
	v_mov_b32_e32 v15, v139
	v_mov_b32_e32 v16, v139
	v_mov_b32_e32 v17, v139
	v_mov_b32_e32 v18, 0
	v_mov_b32_e32 v19, v139
	v_mov_b32_e32 v20, v139
	v_mov_b32_e32 v21, v139
	v_mov_b32_e32 v22, v139
	v_mov_b32_e32 v23, v139
	v_mov_b32_e32 v24, v139
	v_mov_b32_e32 v25, v139
	v_mov_b32_e32 v26, v139
	v_mov_b32_e32 v27, v139
	v_mov_b32_e32 v28, v139
	v_mov_b32_e32 v29, v139
	v_mov_b32_e32 v30, v139
	v_mov_b32_e32 v31, v139
	v_mov_b32_e32 v32, v139
	v_mov_b32_e32 v33, v139
	v_mov_b32_e32 v34, 0
	v_mov_b32_e32 v35, v139
	v_mov_b32_e32 v36, v139
	v_mov_b32_e32 v37, v139
	v_mov_b32_e32 v38, v139
	v_mov_b32_e32 v39, v139
	v_mov_b32_e32 v40, v139
	v_mov_b32_e32 v41, v139
	v_mov_b32_e32 v42, v139
	v_mov_b32_e32 v43, v139
	v_mov_b32_e32 v44, v139
	v_mov_b32_e32 v45, v139
	v_mov_b32_e32 v46, v139
	v_mov_b32_e32 v47, v139
	v_mov_b32_e32 v48, v139
	v_mov_b32_e32 v49, v139
	v_mov_b32_e32 v50, 0
	v_mov_b32_e32 v51, v139
	v_mov_b32_e32 v52, v139
	v_mov_b32_e32 v53, v139
	v_mov_b32_e32 v54, v139
	v_mov_b32_e32 v55, v139
	v_mov_b32_e32 v56, v139
	v_mov_b32_e32 v57, v139
	v_mov_b32_e32 v58, v139
	v_mov_b32_e32 v59, v139
	v_mov_b32_e32 v60, v139
	v_mov_b32_e32 v61, v139
	v_mov_b32_e32 v62, v139
	v_mov_b32_e32 v63, v139
	v_mov_b32_e32 v64, v139
	v_mov_b32_e32 v65, v139
	s_movk_i32 s23, 0x4000
	s_mov_b32 s28, m0
	s_add_i32 s24, s23, s29
	s_mov_b32 m0, s24
	s_add_i32 s25, s23, s42
	global_load_lds_dwordx4 v[144:145], off
	s_addk_i32 s25, 0xff80
	s_mov_b32 m0, s25
	s_add_i32 s24, s24, 0xc000
	global_load_lds_dwordx4 v[144:145], off offset:128
	s_mov_b32 m0, s24
	s_add_i32 s25, s25, 0xc000
	global_load_lds_dwordx4 v[146:147], off
	s_mov_b32 m0, s25
	v_lshl_add_u64 v[144:145], v[144:145], 0, s[18:19]
	global_load_lds_dwordx4 v[146:147], off offset:128
	s_mov_b32 m0, s28
	v_lshl_add_u64 v[146:147], v[146:147], 0, s[18:19]
	s_waitcnt vmcnt(4) lgkmcnt(0)
	s_barrier
	v_mov_b32_e32 v159, v141
	ds_read_b128 v[210:213], v159
	ds_read_b128 v[214:217], v159 offset:512
	ds_read_b128 v[218:221], v159 offset:2048
	ds_read_b128 v[222:225], v159 offset:2560
	ds_read_b128 v[226:229], v159 offset:4096
	ds_read_b128 v[230:233], v159 offset:4608
	ds_read_b128 v[234:237], v159 offset:6144
	ds_read_b128 v[238:241], v159 offset:6656
	s_waitcnt lgkmcnt(7)
	v_mfma_f32_32x32x16_bf16 v[98:113], v[210:213], v[126:129], v[66:81]
	s_waitcnt lgkmcnt(5)
	v_mfma_f32_32x32x16_bf16 v[98:113], v[218:221], v[122:125], v[98:113]
	s_waitcnt lgkmcnt(3)
	v_mfma_f32_32x32x16_bf16 v[98:113], v[226:229], v[118:121], v[98:113]
	s_waitcnt lgkmcnt(1)
	v_mfma_f32_32x32x16_bf16 v[98:113], v[234:237], v[114:117], v[98:113]
	v_mfma_f32_32x32x16_bf16 v[82:97], v[214:217], v[126:129], v[66:81]
	v_mfma_f32_32x32x16_bf16 v[82:97], v[222:225], v[122:125], v[82:97]
	v_mfma_f32_32x32x16_bf16 v[82:97], v[230:233], v[118:121], v[82:97]
	s_waitcnt lgkmcnt(0)
	v_mfma_f32_32x32x16_bf16 v[82:97], v[238:241], v[114:117], v[82:97]
	s_nop 6
	v_exp_f32_e32 v98, v98
	v_exp_f32_e32 v99, v99
	v_exp_f32_e32 v100, v100
	v_exp_f32_e32 v101, v101
	v_exp_f32_e32 v102, v102
	v_exp_f32_e32 v103, v103
	v_exp_f32_e32 v104, v104
	v_exp_f32_e32 v105, v105
	v_exp_f32_e32 v106, v106
	v_exp_f32_e32 v107, v107
	v_exp_f32_e32 v108, v108
	v_exp_f32_e32 v109, v109
	v_exp_f32_e32 v110, v110
	v_exp_f32_e32 v111, v111
	v_exp_f32_e32 v112, v112
	v_exp_f32_e32 v113, v113
	v_exp_f32_e32 v82, v82
	v_exp_f32_e32 v83, v83
	v_exp_f32_e32 v84, v84
	v_exp_f32_e32 v85, v85
	v_exp_f32_e32 v86, v86
	v_exp_f32_e32 v87, v87
	v_exp_f32_e32 v88, v88
	v_exp_f32_e32 v89, v89
	v_exp_f32_e32 v90, v90
	v_exp_f32_e32 v91, v91
	v_exp_f32_e32 v92, v92
	v_exp_f32_e32 v93, v93
	v_exp_f32_e32 v94, v94
	v_exp_f32_e32 v95, v95
	v_exp_f32_e32 v96, v96
	v_exp_f32_e32 v97, v97
	v_cvt_pk_bf16_f32 v194, v98, v99
	v_cvt_pk_bf16_f32 v195, v100, v101
	v_cvt_pk_bf16_f32 v196, v102, v103
	v_cvt_pk_bf16_f32 v197, v104, v105
	v_cvt_pk_bf16_f32 v198, v106, v107
	v_cvt_pk_bf16_f32 v199, v108, v109
	v_cvt_pk_bf16_f32 v200, v110, v111
	v_cvt_pk_bf16_f32 v201, v112, v113
	v_cvt_pk_bf16_f32 v202, v82, v83
	v_cvt_pk_bf16_f32 v203, v84, v85
	v_cvt_pk_bf16_f32 v204, v86, v87
	v_cvt_pk_bf16_f32 v205, v88, v89
	v_cvt_pk_bf16_f32 v206, v90, v91
	v_cvt_pk_bf16_f32 v207, v92, v93
	v_cvt_pk_bf16_f32 v208, v94, v95
	v_cvt_pk_bf16_f32 v209, v96, v97
	s_mov_b32 s6, 0
.Lat3_loop:
	s_add_i32 s22, s6, 1
	s_cmp_lg_u32 s6, 2
	s_cselect_b32 s22, s22, 0
	s_add_i32 s23, s22, 1
	s_cmp_lg_u32 s22, 2
	s_cselect_b32 s23, s23, 0
	s_lshl_b32 s24, s6, 14
	s_lshl_b32 s25, s22, 14
	s_lshl_b32 s23, s23, 14
	v_add_u32_e32 v248, s24, v153
	v_add_u32_e32 v159, s25, v141
	ds_read_b64_tr_b16 v[168:169], v248 offset:49152
	ds_read_b64_tr_b16 v[170:171], v248 offset:49664
	ds_read_b64_tr_b16 v[172:173], v248 offset:53248
	ds_read_b64_tr_b16 v[174:175], v248 offset:53760
	ds_read_b64_tr_b16 v[176:177], v248 offset:57344
	ds_read_b64_tr_b16 v[178:179], v248 offset:57856
	ds_read_b64_tr_b16 v[180:181], v248 offset:61440
	ds_read_b64_tr_b16 v[182:183], v248 offset:61952
	s_waitcnt vmcnt(0)
	s_barrier
	ds_read_b128 v[210:213], v159
	ds_read_b128 v[218:221], v159 offset:2048
	ds_read_b128 v[226:229], v159 offset:4096
	ds_read_b128 v[234:237], v159 offset:6144
	s_cmp_eq_u32 s4, 1
	s_cbranch_scc1 .Lat3_nodma
	s_mov_b32 s28, m0
	s_add_i32 s24, s23, s29
	s_mov_b32 m0, s24
	s_add_i32 s25, s23, s42
	global_load_lds_dwordx4 v[144:145], off
	s_addk_i32 s25, 0xff80
	s_mov_b32 m0, s25
	s_add_i32 s24, s24, 0xc000
	global_load_lds_dwordx4 v[144:145], off offset:128
	s_mov_b32 m0, s24
	s_add_i32 s25, s25, 0xc000
	global_load_lds_dwordx4 v[146:147], off
	s_mov_b32 m0, s25
	v_lshl_add_u64 v[144:145], v[144:145], 0, s[18:19]
	global_load_lds_dwordx4 v[146:147], off offset:128
	s_mov_b32 m0, s28
	v_lshl_add_u64 v[146:147], v[146:147], 0, s[18:19]
.Lat3_nodma:
	s_waitcnt lgkmcnt(8)
	v_mfma_f32_32x32x16_bf16 v[50:65], v[168:171], v[194:197], v[50:65]
	ds_read_b128 v[214:217], v159 offset:512
	ds_read_b128 v[222:225], v159 offset:2560
	v_add_f32_e32 v246, 0, v98
	v_add_f32_e32 v246, v99, v246
	v_add_f32_e32 v246, v100, v246
	v_add_f32_e32 v246, v101, v246
	v_add_f32_e32 v247, 0, v82
	v_add_f32_e32 v247, v83, v247
	v_mfma_f32_32x32x16_bf16 v[34:49], v[172:175], v[194:197], v[34:49]
	ds_read_b128 v[230:233], v159 offset:4608
	ds_read_b128 v[238:241], v159 offset:6656
	v_add_f32_e32 v246, v102, v246
	v_add_f32_e32 v246, v103, v246
	v_add_f32_e32 v246, v104, v246
	v_add_f32_e32 v246, v105, v246
	v_add_f32_e32 v247, v84, v247
	v_add_f32_e32 v247, v85, v247
	s_waitcnt lgkmcnt(8)
	v_mfma_f32_32x32x16_bf16 v[18:33], v[176:179], v[194:197], v[18:33]
	v_add_f32_e32 v246, v106, v246
	v_add_f32_e32 v246, v107, v246
	v_add_f32_e32 v246, v108, v246
	v_add_f32_e32 v246, v109, v246
	v_add_f32_e32 v247, v86, v247
	v_add_f32_e32 v247, v87, v247
	v_mfma_f32_32x32x16_bf16 v[2:17], v[180:183], v[194:197], v[2:17]
	v_add_f32_e32 v246, v110, v246
	v_add_f32_e32 v246, v111, v246
	v_add_f32_e32 v246, v112, v246
	v_add_f32_e32 v246, v113, v246
	v_add_f32_e32 v247, v88, v247
	v_add_f32_e32 v247, v89, v247
	v_add_f32_e32 v246, v139, v246
	ds_read_b64_tr_b16 v[184:185], v248 offset:50176
	ds_read_b64_tr_b16 v[186:187], v248 offset:50688
	ds_read_b64_tr_b16 v[188:189], v248 offset:54272
	ds_read_b64_tr_b16 v[190:191], v248 offset:54784
	s_waitcnt lgkmcnt(10)
	v_mfma_f32_32x32x16_bf16 v[98:113], v[210:213], v[126:129], v[66:81]
	v_add_f32_e32 v247, v90, v247
	v_add_f32_e32 v247, v91, v247
	v_mfma_f32_32x32x16_bf16 v[98:113], v[218:221], v[122:125], v[98:113]
	v_add_f32_e32 v247, v92, v247
	v_add_f32_e32 v247, v93, v247
	s_waitcnt lgkmcnt(8)
	v_mfma_f32_32x32x16_bf16 v[98:113], v[226:229], v[118:121], v[98:113]
	v_add_f32_e32 v247, v94, v247
	v_add_f32_e32 v247, v95, v247
	v_mfma_f32_32x32x16_bf16 v[98:113], v[234:237], v[114:117], v[98:113]
	v_add_f32_e32 v247, v96, v247
	v_add_f32_e32 v247, v97, v247
	v_add_f32_e32 v139, v246, v247
	ds_read_b64_tr_b16 v[160:161], v248 offset:58368
	ds_read_b64_tr_b16 v[162:163], v248 offset:58880
	ds_read_b64_tr_b16 v[242:243], v248 offset:62464
	ds_read_b64_tr_b16 v[244:245], v248 offset:62976
	s_waitcnt lgkmcnt(4)
	v_mfma_f32_32x32x16_bf16 v[50:65], v[184:187], v[198:201], v[50:65]
	v_mfma_f32_32x32x16_bf16 v[34:49], v[188:191], v[198:201], v[34:49]
	ds_read_b64_tr_b16 v[168:169], v248 offset:51200
	ds_read_b64_tr_b16 v[170:171], v248 offset:51712
	ds_read_b64_tr_b16 v[172:173], v248 offset:55296
	ds_read_b64_tr_b16 v[174:175], v248 offset:55808
	s_waitcnt lgkmcnt(4)
	v_mfma_f32_32x32x16_bf16 v[18:33], v[160:163], v[198:201], v[18:33]
	v_exp_f32_e32 v98, v98
	v_exp_f32_e32 v99, v99
	v_exp_f32_e32 v100, v100
	v_mfma_f32_32x32x16_bf16 v[2:17], v[242:245], v[198:201], v[2:17]
	ds_read_b64_tr_b16 v[176:177], v248 offset:59392
	ds_read_b64_tr_b16 v[178:179], v248 offset:59904
	ds_read_b64_tr_b16 v[180:181], v248 offset:63488
	ds_read_b64_tr_b16 v[182:183], v248 offset:64000
	v_exp_f32_e32 v101, v101
	v_exp_f32_e32 v102, v102
	v_mfma_f32_32x32x16_bf16 v[82:97], v[214:217], v[126:129], v[66:81]
	ds_read_b64_tr_b16 v[184:185], v248 offset:52224
	ds_read_b64_tr_b16 v[186:187], v248 offset:52736
	ds_read_b64_tr_b16 v[188:189], v248 offset:56320
	ds_read_b64_tr_b16 v[190:191], v248 offset:56832
	v_exp_f32_e32 v103, v103
	v_exp_f32_e32 v104, v104
	v_mfma_f32_32x32x16_bf16 v[82:97], v[222:225], v[122:125], v[82:97]
	v_exp_f32_e32 v105, v105
	v_exp_f32_e32 v106, v106
	v_exp_f32_e32 v107, v107
	v_mfma_f32_32x32x16_bf16 v[82:97], v[230:233], v[118:121], v[82:97]
	v_exp_f32_e32 v108, v108
	v_exp_f32_e32 v109, v109
	v_exp_f32_e32 v110, v110
	v_mfma_f32_32x32x16_bf16 v[82:97], v[238:241], v[114:117], v[82:97]
	v_exp_f32_e32 v111, v111
	v_exp_f32_e32 v112, v112
	v_exp_f32_e32 v113, v113
	s_waitcnt lgkmcnt(8)
	v_mfma_f32_32x32x16_bf16 v[50:65], v[168:171], v[202:205], v[50:65]
	v_cvt_pk_bf16_f32 v194, v98, v99
	v_cvt_pk_bf16_f32 v195, v100, v101
	v_cvt_pk_bf16_f32 v196, v102, v103
	v_cvt_pk_bf16_f32 v197, v104, v105
	v_mfma_f32_32x32x16_bf16 v[34:49], v[172:175], v[202:205], v[34:49]
	ds_read_b64_tr_b16 v[160:161], v248 offset:60416
	ds_read_b64_tr_b16 v[162:163], v248 offset:60928
	ds_read_b64_tr_b16 v[242:243], v248 offset:64512
	ds_read_b64_tr_b16 v[244:245], v248 offset:65024
	v_cvt_pk_bf16_f32 v198, v106, v107
	v_cvt_pk_bf16_f32 v199, v108, v109
	v_cvt_pk_bf16_f32 v200, v110, v111
	v_cvt_pk_bf16_f32 v201, v112, v113
	s_waitcnt lgkmcnt(8)
	v_mfma_f32_32x32x16_bf16 v[18:33], v[176:179], v[202:205], v[18:33]
	v_exp_f32_e32 v82, v82
	v_exp_f32_e32 v83, v83
	v_exp_f32_e32 v84, v84
	v_mfma_f32_32x32x16_bf16 v[2:17], v[180:183], v[202:205], v[2:17]
	v_exp_f32_e32 v85, v85
	v_exp_f32_e32 v86, v86
	v_exp_f32_e32 v87, v87
	s_waitcnt lgkmcnt(4)
	v_mfma_f32_32x32x16_bf16 v[50:65], v[184:187], v[206:209], v[50:65]
	v_exp_f32_e32 v88, v88
	v_exp_f32_e32 v89, v89
	v_exp_f32_e32 v90, v90
	v_mfma_f32_32x32x16_bf16 v[34:49], v[188:191], v[206:209], v[34:49]
	v_exp_f32_e32 v91, v91
	v_exp_f32_e32 v92, v92
	v_exp_f32_e32 v93, v93
	s_waitcnt lgkmcnt(0)
	v_mfma_f32_32x32x16_bf16 v[18:33], v[160:163], v[206:209], v[18:33]
	v_exp_f32_e32 v94, v94
	v_exp_f32_e32 v95, v95
	v_exp_f32_e32 v96, v96
	v_mfma_f32_32x32x16_bf16 v[2:17], v[242:245], v[206:209], v[2:17]
	v_exp_f32_e32 v97, v97
	v_cvt_pk_bf16_f32 v202, v82, v83
	v_cvt_pk_bf16_f32 v203, v84, v85
	v_cvt_pk_bf16_f32 v204, v86, v87
	v_cvt_pk_bf16_f32 v205, v88, v89
	v_cvt_pk_bf16_f32 v206, v90, v91
	v_cvt_pk_bf16_f32 v207, v92, v93
	v_cvt_pk_bf16_f32 v208, v94, v95
	v_cvt_pk_bf16_f32 v209, v96, v97
	s_add_i32 s4, s4, -1
	s_mov_b32 s6, s22
	s_cmp_eq_u32 s4, 0
	s_cbranch_scc0 .Lat3_loop
	s_lshl_b32 s24, s6, 14
	v_add_u32_e32 v248, s24, v153
	ds_read_b64_tr_b16 v[168:169], v248 offset:49152
	ds_read_b64_tr_b16 v[170:171], v248 offset:49664
	ds_read_b64_tr_b16 v[172:173], v248 offset:53248
	ds_read_b64_tr_b16 v[174:175], v248 offset:53760
	ds_read_b64_tr_b16 v[176:177], v248 offset:57344
	ds_read_b64_tr_b16 v[178:179], v248 offset:57856
	ds_read_b64_tr_b16 v[180:181], v248 offset:61440
	ds_read_b64_tr_b16 v[182:183], v248 offset:61952
	s_waitcnt lgkmcnt(6)
	v_mfma_f32_32x32x16_bf16 v[50:65], v[168:171], v[194:197], v[50:65]
	v_add_f32_e32 v246, 0, v98
	v_add_f32_e32 v247, 0, v82
	v_add_f32_e32 v246, v99, v246
	v_add_f32_e32 v247, v83, v247
	s_waitcnt lgkmcnt(4)
	v_mfma_f32_32x32x16_bf16 v[34:49], v[172:175], v[194:197], v[34:49]
	ds_read_b64_tr_b16 v[184:185], v248 offset:50176
	ds_read_b64_tr_b16 v[186:187], v248 offset:50688
	ds_read_b64_tr_b16 v[188:189], v248 offset:54272
	ds_read_b64_tr_b16 v[190:191], v248 offset:54784
	v_add_f32_e32 v246, v100, v246
	v_add_f32_e32 v247, v84, v247
	v_add_f32_e32 v246, v101, v246
	v_add_f32_e32 v247, v85, v247
	s_waitcnt lgkmcnt(6)
	v_mfma_f32_32x32x16_bf16 v[18:33], v[176:179], v[194:197], v[18:33]
	v_add_f32_e32 v246, v102, v246
	v_add_f32_e32 v247, v86, v247
	v_add_f32_e32 v246, v103, v246
	v_add_f32_e32 v247, v87, v247
	s_waitcnt lgkmcnt(4)
	v_mfma_f32_32x32x16_bf16 v[2:17], v[180:183], v[194:197], v[2:17]
	ds_read_b64_tr_b16 v[160:161], v248 offset:58368
	ds_read_b64_tr_b16 v[162:163], v248 offset:58880
	ds_read_b64_tr_b16 v[242:243], v248 offset:62464
	ds_read_b64_tr_b16 v[244:245], v248 offset:62976
	v_add_f32_e32 v246, v104, v246
	v_add_f32_e32 v247, v88, v247
	v_add_f32_e32 v246, v105, v246
	v_add_f32_e32 v247, v89, v247
	s_waitcnt lgkmcnt(6)
	v_mfma_f32_32x32x16_bf16 v[50:65], v[184:187], v[198:201], v[50:65]
	v_add_f32_e32 v246, v106, v246
	v_add_f32_e32 v247, v90, v247
	v_add_f32_e32 v246, v107, v246
	v_add_f32_e32 v247, v91, v247
	s_waitcnt lgkmcnt(4)
	v_mfma_f32_32x32x16_bf16 v[34:49], v[188:191], v[198:201], v[34:49]
	ds_read_b64_tr_b16 v[168:169], v248 offset:51200
	ds_read_b64_tr_b16 v[170:171], v248 offset:51712
	ds_read_b64_tr_b16 v[172:173], v248 offset:55296
	ds_read_b64_tr_b16 v[174:175], v248 offset:55808
	v_add_f32_e32 v246, v108, v246
	v_add_f32_e32 v247, v92, v247
	v_add_f32_e32 v246, v109, v246
	v_add_f32_e32 v247, v93, v247
	s_waitcnt lgkmcnt(6)
	v_mfma_f32_32x32x16_bf16 v[18:33], v[160:163], v[198:201], v[18:33]
	v_add_f32_e32 v246, v110, v246
	v_add_f32_e32 v247, v94, v247
	v_add_f32_e32 v246, v111, v246
	v_add_f32_e32 v247, v95, v247
	s_waitcnt lgkmcnt(4)
	v_mfma_f32_32x32x16_bf16 v[2:17], v[242:245], v[198:201], v[2:17]
	ds_read_b64_tr_b16 v[176:177], v248 offset:59392
	ds_read_b64_tr_b16 v[178:179], v248 offset:59904
	ds_read_b64_tr_b16 v[180:181], v248 offset:63488
	ds_read_b64_tr_b16 v[182:183], v248 offset:64000
	v_add_f32_e32 v246, v112, v246
	v_add_f32_e32 v247, v96, v247
	v_add_f32_e32 v246, v113, v246
	v_add_f32_e32 v247, v97, v247
	v_add_f32_e32 v246, v139, v246
	v_add_f32_e32 v139, v246, v247
	v_mov_b32_e32 v90, v139
	ds_bpermute_b32 v91, v1, v90
	s_cmp_eq_u32 s41, 0
	s_cselect_b64 s[4:5], -1, 0
	s_waitcnt lgkmcnt(7)
	v_mfma_f32_32x32x16_bf16 v[50:65], v[168:171], v[202:205], v[50:65]
	s_waitcnt lgkmcnt(5)
	v_mfma_f32_32x32x16_bf16 v[34:49], v[172:175], v[202:205], v[34:49]
	ds_read_b64_tr_b16 v[184:185], v248 offset:52224
	ds_read_b64_tr_b16 v[186:187], v248 offset:52736
	ds_read_b64_tr_b16 v[188:189], v248 offset:56320
	ds_read_b64_tr_b16 v[190:191], v248 offset:56832
	s_waitcnt lgkmcnt(7)
	v_mfma_f32_32x32x16_bf16 v[18:33], v[176:179], v[202:205], v[18:33]
	s_waitcnt lgkmcnt(5)
	v_mfma_f32_32x32x16_bf16 v[2:17], v[180:183], v[202:205], v[2:17]
	ds_read_b64_tr_b16 v[160:161], v248 offset:60416
	ds_read_b64_tr_b16 v[162:163], v248 offset:60928
	ds_read_b64_tr_b16 v[242:243], v248 offset:64512
	ds_read_b64_tr_b16 v[244:245], v248 offset:65024
	s_waitcnt lgkmcnt(6)
	v_mfma_f32_32x32x16_bf16 v[50:65], v[184:187], v[206:209], v[50:65]
	s_waitcnt lgkmcnt(4)
	v_mfma_f32_32x32x16_bf16 v[34:49], v[188:191], v[206:209], v[34:49]
	s_waitcnt lgkmcnt(2)
	v_mfma_f32_32x32x16_bf16 v[18:33], v[160:163], v[206:209], v[18:33]
	s_waitcnt lgkmcnt(0)
	v_mfma_f32_32x32x16_bf16 v[2:17], v[242:245], v[206:209], v[2:17]
	v_add_f32_e32 v90, v90, v91
	v_cndmask_b32_e64 v91, v148, 1.0, s[4:5]
	v_div_scale_f32 v92, s[22:23], v90, v90, v91
	v_rcp_f32_e32 v93, v92
	s_waitcnt vmcnt(0) lgkmcnt(0)
	s_barrier
	v_fma_f32 v74, -v92, v93, 1.0
	v_fmac_f32_e32 v93, v74, v93
	v_div_scale_f32 v74, vcc, v91, v90, v91
	v_mul_f32_e32 v75, v74, v93
	v_fma_f32 v76, -v92, v75, v74
	v_fmac_f32_e32 v75, v76, v93
	v_fma_f32 v66, -v92, v75, v74
	s_nop 0
	v_div_fmas_f32 v66, v66, v93, v75
	v_div_fixup_f32 v82, v66, v90, v91
	v_lshl_add_u32 v70, s27, 13, v150
	s_and_b64 vcc, exec, s[4:5]
	s_cbranch_vccnz .LBB0_991
	v_mul_f32_e32 v66, v50, v82
	v_mul_f32_e32 v67, v51, v82
	v_cvt_pk_f16_f32 v66, v66, v67
	v_mul_f32_e32 v67, v52, v82
	v_mul_f32_e32 v68, v53, v82
	v_cvt_pk_f16_f32 v67, v67, v68
	ds_write2st64_b32 v70, v66, v67 offset1:1
	v_mul_f32_e32 v66, v54, v82
	v_mul_f32_e32 v67, v55, v82
	v_cvt_pk_f16_f32 v66, v66, v67
	v_mul_f32_e32 v67, v56, v82
	v_mul_f32_e32 v68, v57, v82
	v_cvt_pk_f16_f32 v67, v67, v68
	ds_write2st64_b32 v70, v66, v67 offset0:2 offset1:3
	v_mul_f32_e32 v66, v58, v82
	v_mul_f32_e32 v67, v59, v82
	v_cvt_pk_f16_f32 v66, v66, v67
	v_mul_f32_e32 v67, v60, v82
	v_mul_f32_e32 v68, v61, v82
	v_cvt_pk_f16_f32 v67, v67, v68
	ds_write2st64_b32 v70, v66, v67 offset0:4 offset1:5
	v_mul_f32_e32 v66, v62, v82
	v_mul_f32_e32 v67, v63, v82
	v_cvt_pk_f16_f32 v66, v66, v67
	v_mul_f32_e32 v67, v64, v82
	v_mul_f32_e32 v68, v65, v82
	v_cvt_pk_f16_f32 v67, v67, v68
	ds_write2st64_b32 v70, v66, v67 offset0:6 offset1:7
	v_mul_f32_e32 v66, v34, v82
	v_mul_f32_e32 v67, v35, v82
	v_cvt_pk_f16_f32 v66, v66, v67
	v_mul_f32_e32 v67, v36, v82
	v_mul_f32_e32 v68, v37, v82
	v_cvt_pk_f16_f32 v67, v67, v68
	ds_write2st64_b32 v70, v66, v67 offset0:8 offset1:9
	v_mul_f32_e32 v66, v38, v82
	v_mul_f32_e32 v67, v39, v82
	v_cvt_pk_f16_f32 v66, v66, v67
	v_mul_f32_e32 v67, v40, v82
	v_mul_f32_e32 v68, v41, v82
	v_cvt_pk_f16_f32 v67, v67, v68
	ds_write2st64_b32 v70, v66, v67 offset0:10 offset1:11
	v_mul_f32_e32 v66, v42, v82
	v_mul_f32_e32 v67, v43, v82
	v_cvt_pk_f16_f32 v66, v66, v67
	v_mul_f32_e32 v67, v44, v82
	v_mul_f32_e32 v68, v45, v82
	v_cvt_pk_f16_f32 v67, v67, v68
	ds_write2st64_b32 v70, v66, v67 offset0:12 offset1:13
	v_mul_f32_e32 v66, v46, v82
	v_mul_f32_e32 v67, v47, v82
	v_cvt_pk_f16_f32 v66, v66, v67
	v_mul_f32_e32 v67, v48, v82
	v_mul_f32_e32 v68, v49, v82
	v_cvt_pk_f16_f32 v67, v67, v68
	ds_write2st64_b32 v70, v66, v67 offset0:14 offset1:15
	v_mul_f32_e32 v66, v18, v82
	v_mul_f32_e32 v67, v19, v82
	v_cvt_pk_f16_f32 v66, v66, v67
	v_mul_f32_e32 v67, v20, v82
	v_mul_f32_e32 v68, v21, v82
	v_cvt_pk_f16_f32 v67, v67, v68
	ds_write2st64_b32 v70, v66, v67 offset0:16 offset1:17
	v_mul_f32_e32 v66, v22, v82
	v_mul_f32_e32 v67, v23, v82
	v_cvt_pk_f16_f32 v66, v66, v67
	v_mul_f32_e32 v67, v24, v82
	v_mul_f32_e32 v68, v25, v82
	v_cvt_pk_f16_f32 v67, v67, v68
	ds_write2st64_b32 v70, v66, v67 offset0:18 offset1:19
	v_mul_f32_e32 v66, v26, v82
	v_mul_f32_e32 v67, v27, v82
	v_cvt_pk_f16_f32 v66, v66, v67
	v_mul_f32_e32 v67, v28, v82
	v_mul_f32_e32 v68, v29, v82
	v_cvt_pk_f16_f32 v67, v67, v68
	ds_write2st64_b32 v70, v66, v67 offset0:20 offset1:21
	v_mul_f32_e32 v66, v30, v82
	v_mul_f32_e32 v67, v31, v82
	v_cvt_pk_f16_f32 v66, v66, v67
	v_mul_f32_e32 v67, v32, v82
	v_mul_f32_e32 v68, v33, v82
	v_cvt_pk_f16_f32 v67, v67, v68
	ds_write2st64_b32 v70, v66, v67 offset0:22 offset1:23
	v_mul_f32_e32 v66, v2, v82
	v_mul_f32_e32 v67, v3, v82
	v_cvt_pk_f16_f32 v66, v66, v67
	v_mul_f32_e32 v67, v4, v82
	v_mul_f32_e32 v68, v5, v82
	v_cvt_pk_f16_f32 v67, v67, v68
	ds_write2st64_b32 v70, v66, v67 offset0:24 offset1:25
	v_mul_f32_e32 v66, v6, v82
	v_mul_f32_e32 v67, v7, v82
	v_cvt_pk_f16_f32 v66, v66, v67
	v_mul_f32_e32 v67, v8, v82
	v_mul_f32_e32 v68, v9, v82
	v_cvt_pk_f16_f32 v67, v67, v68
	ds_write2st64_b32 v70, v66, v67 offset0:26 offset1:27
	v_mul_f32_e32 v66, v10, v82
	v_mul_f32_e32 v67, v11, v82
	v_cvt_pk_f16_f32 v66, v66, v67
	v_mul_f32_e32 v67, v12, v82
	v_mul_f32_e32 v68, v13, v82
	v_cvt_pk_f16_f32 v67, v67, v68
	ds_write2st64_b32 v70, v66, v67 offset0:28 offset1:29
	v_mul_f32_e32 v66, v14, v82
	v_mul_f32_e32 v67, v15, v82
	v_cvt_pk_f16_f32 v66, v66, v67
	v_mul_f32_e32 v67, v16, v82
	v_mul_f32_e32 v68, v17, v82
	v_cvt_pk_f16_f32 v67, v67, v68
	ds_write2st64_b32 v70, v66, v67 offset0:30 offset1:31
